# merge epilogue: warm L2 for batches 2-4 gate rows with early plain loads while batch 1 is in flight; first batch wait counted
# baseline (speedup 1.0000x reference)
; DEV float bf2f(u16 h) { return __uint_as_float(((unsigned)h) << 16); }
; DEV float sigm_f(float v) { return 1.f / (1.f + __expf(-v)); }
; DEV void phase_gemm(const Params& p, int l, int mode) {
;     ...
;       } else if (mode == 1) {
;         const u16* MG = (const u16*)(ws + OFF_MG);
;         u16* MH = (u16*)(ws + OFF_KROW); u16* MB = (u16*)(ws + OFF_VT);
;         const bool ex = cur.extra != 0;
;         const bool rd = !ex && sb > 0;
;     ...
; #pragma unroll
;         for (int hb = 0; hb < 4; ++hb) {
;           bf16x8 g[4], pm_[4];
; #pragma unroll
;           for (int qq = 0; qq < 4; ++qq) { M1_ADDR(hb * 4 + qq); g[qq] = __builtin_nontemporal_load(reinterpret_cast<const bf16x8*>(MG + R_ * 3072 + sb * 1024 + cc_)); pm_[qq] = *reinterpret_cast<const bf16x8*>(MH + R_ * 1024 + cc_); }
; #pragma unroll
;           for (int qq = 0; qq < 4; ++qq) {
;             M1_ADDR(hb * 4 + qq);
;             f32x4 v0 = acc[ai_][bj_][m_][0], v1 = acc[ai_][bj_][m_][1];
; #pragma unroll
;             for (int e = 0; e < 4; ++e) { v0[e] *= sigm_f(bf2f((u16)g[qq][e])); v1[e] *= sigm_f(bf2f((u16)g[qq][4 + e])); }
;             if (ex) {
;               float* mp = (float*)(ws + OFF_MFC) + ((size_t)sb * 1024 + (R_ - ROWS_LAT)) * 1024 + cc_;
;               *reinterpret_cast<f32x4*>(mp) = v0; *reinterpret_cast<f32x4*>(mp + 4) = v1;
.LBB0_241:
	s_andn2_b64 vcc, exec, s[4:5]
	s_cbranch_vccnz .LBB0_339
	s_add_u32 s8, s96, 0xfe00000
	s_addc_u32 s9, s97, 0
	s_add_u32 s3, s96, 0x14200000
	s_addc_u32 s14, s97, 0
	s_cmp_lg_u32 s23, 0
	s_cselect_b64 s[16:17], -1, 0
	s_cmp_gt_i32 s0, 0
	s_cselect_b64 s[12:13], -1, 0
	s_lshl_b32 s4, s0, 10
	s_ashr_i32 s5, s4, 31
	s_lshl_b64 s[4:5], s[4:5], 1
	s_add_u32 s1, s96, s4
	s_addc_u32 s4, s97, s5
	s_add_u32 s10, s1, 0x2b800000
	s_addc_u32 s11, s4, 0
	s_ashr_i32 s1, s0, 31
	s_lshl_b64 s[4:5], s[0:1], 22
	s_add_u32 s4, s96, s4
	v_lshlrev_b32_e32 v16, 5, v226
	v_lshlrev_b32_e32 v17, 3, v227
	s_addc_u32 s5, s97, s5
	v_ashrrev_i32_e32 v175, 31, v174
	v_or3_b32 v168, v16, v17, s22
	v_or_b32_e32 v178, 16, v174
	s_cmp_lt_i32 s0, 2
	v_ashrrev_i32_e32 v169, 31, v168
	v_lshlrev_b64 v[180:181], 11, v[174:175]
	v_ashrrev_i32_e32 v179, 31, v178
	s_cselect_b32 s0, s8, s3
	v_mov_b64_e32 v[16:17], s[10:11]
	s_movk_i32 s3, 0x1800
	v_lshlrev_b64 v[172:173], 1, v[168:169]
	v_lshl_add_u64 v[128:129], s[8:9], 0, v[180:181]
	v_lshlrev_b64 v[176:177], 11, v[178:179]
	s_cselect_b32 s1, s9, s14
	v_mad_i64_i32 v[18:19], s[14:15], v174, s3, v[16:17]
	v_lshl_add_u64 v[170:171], v[128:129], 0, v[172:173]
	v_mad_i64_i32 v[16:17], s[14:15], v178, s3, v[16:17]
	v_lshl_add_u64 v[128:129], s[8:9], 0, v[176:177]
	v_lshl_add_u64 v[18:19], v[18:19], 0, v[172:173]
	v_lshl_add_u64 v[16:17], v[16:17], 0, v[172:173]
	v_lshl_add_u64 v[128:129], v[128:129], 0, v[172:173]
	global_load_dwordx4 v[148:151], v[18:19], off offset:256 nt
	global_load_dwordx4 v[144:147], v[170:171], off offset:256
	global_load_dwordx4 v[140:143], v[16:17], off nt
	global_load_dwordx4 v[136:139], v[128:129], off
	global_load_dwordx4 v[132:135], v[16:17], off offset:256 nt
	s_nop 0
	global_load_dwordx4 v[128:131], v[128:129], off offset:256
	s_nop 0
	global_load_dwordx4 v[154:157], v[18:19], off nt
	s_mov_b64 s[14:15], 0x30000
	v_lshl_add_u64 v[248:249], v[18:19], 0, s[14:15]
	v_lshl_add_u64 v[250:251], v[16:17], 0, s[14:15]
	global_load_dwordx4 v[244:247], v[248:249], off
	global_load_dwordx4 v[244:247], v[248:249], off offset:256
	global_load_dwordx4 v[244:247], v[250:251], off
	global_load_dwordx4 v[244:247], v[250:251], off offset:256
	s_mov_b64 s[14:15], 0xc0000
	v_lshl_add_u64 v[248:249], v[18:19], 0, s[14:15]
	v_lshl_add_u64 v[250:251], v[16:17], 0, s[14:15]
	global_load_dwordx4 v[244:247], v[248:249], off
	global_load_dwordx4 v[244:247], v[248:249], off offset:256
	global_load_dwordx4 v[244:247], v[250:251], off
	global_load_dwordx4 v[244:247], v[250:251], off offset:256
	s_mov_b64 s[14:15], 0xf0000
	v_lshl_add_u64 v[248:249], v[18:19], 0, s[14:15]
	v_lshl_add_u64 v[250:251], v[16:17], 0, s[14:15]
	global_load_dwordx4 v[244:247], v[248:249], off
	global_load_dwordx4 v[244:247], v[248:249], off offset:256
	global_load_dwordx4 v[244:247], v[250:251], off
	global_load_dwordx4 v[244:247], v[250:251], off offset:256
	s_cmp_eq_u32 s23, 0
	s_waitcnt vmcnt(12)
	v_lshlrev_b32_e32 v17, 16, v156
	v_mul_f32_e32 v17, 0xbfb8aa3b, v17
	v_lshlrev_b32_e32 v16, 16, v154
	v_exp_f32_e32 v18, v17
	v_and_b32_e32 v17, 0xffff0000, v154
	v_mul_f32_e32 v16, 0xbfb8aa3b, v16
	v_mul_f32_e32 v17, 0xbfb8aa3b, v17
	v_exp_f32_e32 v16, v16
	v_exp_f32_e32 v17, v17
	s_nop 0
	v_pk_add_f32 v[16:17], v[16:17], 1.0 op_sel_hi:[1,0]
	s_nop 0
	s_nop 0
	v_rcp_f32_e32 v17, v17
	s_nop 0
	s_nop 0
	v_rcp_f32_e32 v16, v16
	s_nop 0
	v_pk_mul_f32 v[152:153], v[120:121], v[16:17]
	v_and_b32_e32 v16, 0xffff0000, v156
	v_mul_f32_e32 v16, 0xbfb8aa3b, v16
	v_exp_f32_e32 v19, v16
	s_nop 0
	v_pk_add_f32 v[16:17], v[18:19], 1.0 op_sel_hi:[1,0]
	s_nop 0
	s_nop 0
	v_rcp_f32_e32 v17, v17
	s_nop 0
	s_nop 0
	v_rcp_f32_e32 v16, v16
	s_nop 0
	v_pk_mul_f32 v[158:159], v[112:113], v[16:17]
	v_lshlrev_b32_e32 v17, 16, v157
	v_mul_f32_e32 v17, 0xbfb8aa3b, v17
	v_lshlrev_b32_e32 v16, 16, v155
	v_exp_f32_e32 v18, v17
	v_and_b32_e32 v17, 0xffff0000, v155
	v_mul_f32_e32 v16, 0xbfb8aa3b, v16
	v_mul_f32_e32 v17, 0xbfb8aa3b, v17
	v_exp_f32_e32 v16, v16
	v_exp_f32_e32 v17, v17
	s_nop 0
	v_pk_add_f32 v[16:17], v[16:17], 1.0 op_sel_hi:[1,0]
	s_nop 0
	s_nop 0
	v_rcp_f32_e32 v17, v17
	s_nop 0
	s_nop 0
	v_rcp_f32_e32 v16, v16
	s_nop 0
	v_pk_mul_f32 v[154:155], v[122:123], v[16:17]
	v_and_b32_e32 v16, 0xffff0000, v157
	v_mul_f32_e32 v16, 0xbfb8aa3b, v16
	v_exp_f32_e32 v19, v16
	s_nop 0
	v_pk_add_f32 v[16:17], v[18:19], 1.0 op_sel_hi:[1,0]
	s_nop 0
	s_nop 0
	v_rcp_f32_e32 v17, v17
	s_nop 0
	s_nop 0
	v_rcp_f32_e32 v16, v16
	s_nop 0
	v_pk_mul_f32 v[160:161], v[114:115], v[16:17]
	v_lshlrev_b64 v[16:17], 12, v[174:175]
	v_lshl_add_u64 v[182:183], s[4:5], 0, v[16:17]
	s_cbranch_scc1 .LBB0_244
	v_lshl_add_u64 v[16:17], v[168:169], 2, v[182:183]
	v_lshl_add_u64 v[18:19], v[16:17], 0, s[52:53]
	v_add_co_u32_e32 v16, vcc, 0x36649000, v16
	s_nop 1
	v_addc_co_u32_e32 v17, vcc, 0, v17, vcc
	global_store_dwordx4 v[16:17], v[152:155], off offset:1792
	global_store_dwordx4 v[18:19], v[158:161], off offset:16
	v_cndmask_b32_e64 v16, 0, 1, s[12:13]
	v_cmp_ne_u32_e64 s[12:13], 1, v16
	s_cbranch_execz .LBB0_245
	s_branch .LBB0_248
